# group A MFMA phase at priority 2; Q-load drain before first DMA group removed
# speedup vs baseline: 1.0062x; 1.0062x over previous
; DI void diff_core(unsigned char* smem, const u16* qptr, const u16* kbase, const u16* vtbase, int vld,
;                   int ntb, int ntw, int nvalid, int ks0, const float* lut, int qpos, bool active, bool grpB,
;                   f32x16 (&O)[4], float& l_out) {
;     ...
;   unsigned ksrc[2], vsrc[2];
; #pragma unroll
;   for (int i = 0; i < 2; ++i) {
;     const int ci = (i * 8 + w) * 64 + lane;
;     const int krow = ci >> 4, kc = (ci & 15) ^ (krow & 15);
;     ksrc[i] = (unsigned)(krow * kld + kc * 8) * 2u;
;     const int vrow = ci >> 3, vc = (ci & 7) ^ ((vrow >> 1) & 7);
;     vsrc[i] = (unsigned)(vrow * vld + vc * 8) * 2u;
;   }
;   auto dma_piece = [&](int t, int slot, int piece) {
;     LAS unsigned char* b = lds + slot * D_SLOT + w * 1024;
;     const char* kt = (const char*)kbase + (size_t)(64 * t) * kld * 2;
;     const char* vt = (const char*)vtbase + (size_t)(64 * t) * 2;
;     if (piece == 0) __builtin_amdgcn_global_load_lds((const unsigned*)(kt + ksrc[0]), (LAS unsigned*)(b), 16, 0, 0);
;     else if (piece == 1) __builtin_amdgcn_global_load_lds((const unsigned*)(kt + ksrc[1]), (LAS unsigned*)(b + 8192), 16, 0, 0);
;     else if (piece == 2) __builtin_amdgcn_global_load_lds((const unsigned*)(vt + vsrc[0]), (LAS unsigned*)(b + 16384), 16, 0, 0);
;     else __builtin_amdgcn_global_load_lds((const unsigned*)(vt + vsrc[1]), (LAS unsigned*)(b + 24576), 16, 0, 0);
; __device__ void diff_item(const Params& p, unsigned char* smem, bool sample, int b, int h, int qb, float lam) {
;     ...
;   if (!sample) {
;     const int s = qb * 128 + g * 32 + r;
;     tok = b * SEQ + s;
;     qpos = s - r;
;     ntw = 2 * qb + (g >> 1) + 1;
;     ntb = 2 * qb + 2;
;     nvalid = 64;
;     active = true; valid = true;
;     kbase = p.Kall + (size_t)b * SEQ * 1024 + h * 128;
;     vtbase = p.VTp + (size_t)(b * 1024 + h * 128) * SEQ;
;     vld = SEQ;
;   } else {
;     tok = NPROMPT + b * 16 + (r < 16 ? r : 15);
;     qpos = 1024;
;     ntw = 17; ntb = 17; nvalid = 16;
;     active = (g == 0); valid = (r < 16);
;     kbase = p.Kall + ((size_t)NPROMPT + (size_t)b * SKV) * 1024 + h * 128;
;     vtbase = p.VTs + (size_t)(b * 1024 + h * 128) * SKV;
;     vld = SKV;
;   }
;   const u16* qptr = p.Qb + (size_t)tok * 1024 + h * 128 + c * 64 + hh * 8;
;   f32x16 O[4];
;   float l;
;   diff_core(smem, qptr, kbase, vtbase, vld, ntb, ntw, nvalid, 4 * c, lut, qpos + r, active, c == 1, O, l);
.LBB0_344:
	s_or_b64 exec, exec, s[0:1]
	s_waitcnt lgkmcnt(0)
	s_barrier
	ds_read_b32 v0, v172
	s_movk_i32 s0, 0xff
	s_waitcnt lgkmcnt(0)
	s_barrier
	v_cmp_lt_i32_e32 vcc, s0, v0
	v_readfirstlane_b32 s6, v0
	s_mov_b64 s[0:1], -1
	s_cbranch_vccnz .LBB0_339
	v_mov_b32_e32 v175, v160
	s_ashr_i32 s62, s6, 1
	s_and_b32 s59, s6, 1
	v_readfirstlane_b32 s56, v175
	s_sub_i32 s0, 0x7f, s62
	s_bfe_u32 s39, s56, 0x20006
	s_or_b32 s57, s59, s33
	s_lshl_b32 s1, s0, 7
	s_lshl_b32 s6, s39, 5
	s_lshl_b32 s0, s0, 1
	v_and_b32_e32 v182, 31, v175
	s_ashr_i32 s64, s56, 8
	s_or_b32 s63, s6, s1
	s_or_b32 s58, s0, 1
	s_lshl_b32 s6, s57, 8
	v_or_b32_e32 v0, s34, v182
	s_add_u32 s14, s36, s6
	v_add_u32_e32 v0, s63, v0
	s_addc_u32 s15, s37, 0
	s_lshl_b32 s0, s57, 22
	s_or_b32 s0, s0, s35
	v_ashrrev_i32_e32 v1, 31, v0
	v_readlane_b32 s40, v255, 0
	s_add_u32 s20, s68, s0
	v_lshlrev_b64 v[164:165], 11, v[0:1]
	v_readlane_b32 s52, v255, 12
	v_readlane_b32 s53, v255, 13
	s_addc_u32 s21, s69, 0
	s_lshl_b32 s0, s64, 6
	v_lshl_add_u64 v[0:1], s[52:53], 0, v[164:165]
	v_bfe_u32 v174, v175, 5, 1
	v_lshl_add_u64 v[0:1], v[0:1], 0, s[6:7]
	s_ashr_i32 s1, s0, 31
	v_lshl_add_u64 v[0:1], s[0:1], 1, v[0:1]
	v_lshlrev_b32_e32 v162, 4, v174
	v_lshl_add_u64 v[2:3], v[0:1], 0, v[162:163]
	v_mov_b32_e32 v0, v160
	global_load_dwordx4 v[128:131], v[2:3], off
	global_load_dwordx4 v[132:135], v[2:3], off offset:32
	global_load_dwordx4 v[136:139], v[2:3], off offset:64
	global_load_dwordx4 v[140:143], v[2:3], off offset:96
	v_readfirstlane_b32 s1, v0
	s_movk_i32 s0, 0xffc0
	s_cmp_eq_u32 s64, 1
	v_mov_b32_e32 v1, s1
	v_bfi_b32 v1, s0, v1, v0
	s_cselect_b64 s[12:13], -1, 0
	s_cmp_lg_u32 s64, 1
	v_ashrrev_i32_e32 v2, 4, v1
	v_lshrrev_b32_e32 v3, 4, v1
	v_lshlrev_b32_e32 v4, 11, v1
	v_add_u32_e32 v1, 0x200, v1
	s_cselect_b64 s[16:17], -1, 0
	s_lshl_b32 s0, s1, 4
	v_xor_b32_e32 v5, v2, v0
	v_lshlrev_b32_e32 v6, 11, v2
	v_xor_b32_e32 v2, v3, v0
	v_ashrrev_i32_e32 v3, 4, v1
	s_and_b32 s0, s0, 0xfffffc00
	v_lshlrev_b32_e32 v7, 4, v5
	v_lshlrev_b32_e32 v2, 3, v2
	v_xor_b32_e32 v5, v3, v0
	s_add_i32 s6, s0, 0
	v_lshlrev_b32_e32 v3, 11, v3
	v_and_b32_e32 v2, 56, v2
	v_lshlrev_b32_e32 v5, 4, v5
	v_and_or_b32 v162, v7, s3, v6
	s_mov_b32 m0, s6
	v_lshlrev_b32_e32 v1, 11, v1
	v_and_or_b32 v4, v4, s22, v2
	v_and_or_b32 v170, v5, s3, v3
	v_and_or_b32 v1, v1, s22, v2
	v_lshlrev_b32_e32 v166, 1, v4
	v_lshlrev_b32_e32 v168, 1, v1
	v_mov_b32_e32 v167, v163
	v_mov_b32_e32 v169, v163
	v_lshl_add_u64 v[2:3], s[20:21], 0, v[166:167]
	v_lshl_add_u64 v[4:5], s[20:21], 0, v[168:169]
	v_lshl_add_u64 v[2:3], v[2:3], 0, s[8:9]
	v_lshl_add_u64 v[4:5], v[4:5], 0, s[8:9]
	v_mov_b32_e32 v171, v163
	v_readlane_b32 s41, v255, 1
	v_readlane_b32 s42, v255, 2
	v_readlane_b32 s43, v255, 3
	v_readlane_b32 s44, v255, 4
	v_readlane_b32 s45, v255, 5
	v_readlane_b32 s46, v255, 6
	v_readlane_b32 s47, v255, 7
	v_readlane_b32 s48, v255, 8
	v_readlane_b32 s49, v255, 9
	v_readlane_b32 s50, v255, 10
	v_readlane_b32 s51, v255, 11
	v_readlane_b32 s54, v255, 14
	v_readlane_b32 s55, v255, 15
	s_nop 0
	s_nop 0
	global_load_lds_dwordx4 v162, s[14:15]
	s_add_i32 m0, s6, 0x2000
	s_nop 0
	global_load_lds_dwordx4 v170, s[14:15]
	s_add_i32 m0, s6, 0x4000
	s_nop 0
	global_load_lds_dwordx4 v166, s[20:21]
	s_add_i32 m0, s6, 0x6000
	s_nop 0
	global_load_lds_dwordx4 v168, s[20:21]
	s_add_i32 m0, s6, 0x8000
	s_add_u32 s0, s14, 0x20000
	s_addc_u32 s1, s15, 0
	global_load_lds_dwordx4 v162, s[0:1]
	s_add_i32 m0, s6, 0xa000
	s_and_b64 vcc, exec, s[12:13]
	global_load_lds_dwordx4 v170, s[0:1]
	s_add_i32 m0, s6, 0xc000
	s_mov_b64 s[0:1], -1
	global_load_lds_dwordx4 v[2:3], off
	s_add_i32 m0, s6, 0xe000
	s_nop 0
	global_load_lds_dwordx4 v[4:5], off
	s_min_u32 s65, s58, 2
	s_add_i32 m0, s6, 0x10000
	s_lshl_b32 s0, s65, 17
	s_add_u32 s0, s14, s0
	s_addc_u32 s1, s15, 0
	v_lshl_add_u64 v[2:3], s[0:1], 0, v[162:163]
	s_lshl_b32 s65, s65, 7
	global_load_lds_dwordx4 v[2:3], off
	s_add_i32 m0, s6, 0x12000
	v_lshl_add_u64 v[2:3], s[0:1], 0, v[170:171]
	s_add_u32 s0, s20, s65
	s_addc_u32 s1, s21, 0
	global_load_lds_dwordx4 v[2:3], off
	v_lshl_add_u64 v[2:3], s[0:1], 0, v[166:167]
	s_add_i32 m0, s6, 0x14000
	s_nop 0
	global_load_lds_dwordx4 v[2:3], off
	v_lshl_add_u64 v[2:3], s[0:1], 0, v[168:169]
	s_add_i32 m0, s6, 0x16000
	s_mov_b64 s[0:1], 0
	global_load_lds_dwordx4 v[2:3], off
	s_waitcnt vmcnt(8)

; DI void diff_core(unsigned char* smem, const u16* qptr, const u16* kbase, const u16* vtbase, int vld,
;                   int ntb, int ntw, int nvalid, int ks0, const float* lut, int qpos, bool active, bool grpB,
;                   f32x16 (&O)[4], float& l_out) {
;     ...
;   auto qk = [&](int slot) {
;     if (grpB) __builtin_amdgcn_s_setprio(2); else __builtin_amdgcn_s_setprio(1);
;     const float ini = -m;
; #pragma unroll
;     for (int kb = 0; kb < 2; ++kb)
; #pragma unroll
;       for (int e = 0; e < 16; ++e) S[kb][e] = ini;
;     const LAS unsigned char* b = lds + slot * D_SLOT;
;     bf16x8 kf[4][2];
; #pragma unroll
;     ...
;   auto pv = [&](int slot) {
;     if (grpB) __builtin_amdgcn_s_setprio(2); else __builtin_amdgcn_s_setprio(1);
;     const LAS unsigned char* b = lds + slot * D_SLOT;
;     bf16x8 va[4], vb[4];
; #pragma unroll
;     for (int tt = 0; tt < 4; ++tt) va[tt] = *reinterpret_cast<const LAS bf16x8*>(b + voff[0] + tt * 32 * 128);
; #pragma unroll
;     for (int tt = 0; tt < 4; ++tt) vb[tt] = *reinterpret_cast<const LAS bf16x8*>(b + voff[1] + tt * 32 * 128);
;     {
;       const bf16x8 pf = __builtin_bit_cast(bf16x8, P[0]);
; #pragma unroll
;       for (int tt = 0; tt < 4; ++tt) O[tt] = MFMA(va[tt], pf, O[tt]);
;     }
; #pragma unroll
;     for (int tt = 0; tt < 4; ++tt) va[tt] = *reinterpret_cast<const LAS bf16x8*>(b + voff[2] + tt * 32 * 128);
;     {
;       const bf16x8 pf = __builtin_bit_cast(bf16x8, P[1]);
; #pragma unroll
;       for (int tt = 0; tt < 4; ++tt) O[tt] = MFMA(vb[tt], pf, O[tt]);
;     }
; #pragma unroll
;     for (int tt = 0; tt < 4; ++tt) vb[tt] = *reinterpret_cast<const LAS bf16x8*>(b + voff[3] + tt * 32 * 128);
;     {
;       const bf16x8 pf = __builtin_bit_cast(bf16x8, P[2]);
; #pragma unroll
;       for (int tt = 0; tt < 4; ++tt) O[tt] = MFMA(va[tt], pf, O[tt]);
;     }
;     {
;       const bf16x8 pf = __builtin_bit_cast(bf16x8, P[3]);
; #pragma unroll
;       for (int tt = 0; tt < 4; ++tt) O[tt] = MFMA(vb[tt], pf, O[tt]);
;     }
;     __builtin_amdgcn_sched_group_barrier(0x100, 8, 0);
;     __builtin_amdgcn_sched_group_barrier(0x008, 4, 0);
;     __builtin_amdgcn_sched_group_barrier(0x100, 4, 0);
;     __builtin_amdgcn_sched_group_barrier(0x008, 4, 0);
;     __builtin_amdgcn_sched_group_barrier(0x100, 4, 0);
;     __builtin_amdgcn_sched_group_barrier(0x008, 8, 0);
;     __builtin_amdgcn_s_setprio(0);
;   };
.LBB0_360:
	s_add_i32 s66, s64, 0x101
	s_cmp_gt_u32 s66, s16
	s_cbranch_scc1 .LBB0_362
	s_setprio 2
	s_and_b32 s0, s65, 0x18000
	v_add_u32_e32 v248, s0, v197
	ds_read_b128 v[64:67], v248 offset:16384
	ds_read_b128 v[68:71], v248 offset:20480
	ds_read_b128 v[72:75], v248 offset:24576
	ds_read_b128 v[76:79], v248 offset:28672
	s_add_i32 s67, s65, 0xfffe8000
	s_and_b32 s67, s67, 0x18000
	v_cvt_pk_bf16_f32 v144, v96, v97
	v_cvt_pk_bf16_f32 v145, v98, v99
	v_cvt_pk_bf16_f32 v146, v100, v101
	v_cvt_pk_bf16_f32 v147, v102, v103
	v_add_f32_e32 v250, v97, v96
	v_add_f32_e32 v250, v98, v250
	s_waitcnt lgkmcnt(4)
	v_mfma_f32_32x32x16_bf16 v[48:63], v[200:203], v[144:147], v[48:63]
	v_cvt_pk_bf16_f32 v148, v104, v105
	v_add_f32_e32 v250, v99, v250
	v_add_f32_e32 v250, v100, v250
	v_add_u32_e32 v249, s0, v198
	ds_read_b128 v[80:83], v249 offset:16384
	ds_read_b128 v[84:87], v249 offset:20480
	ds_read_b128 v[88:91], v249 offset:24576
	ds_read_b128 v[92:95], v249 offset:28672
	v_mfma_f32_32x32x16_bf16 v[32:47], v[204:207], v[144:147], v[32:47]
	v_cvt_pk_bf16_f32 v149, v106, v107
	v_add_f32_e32 v250, v101, v250
	v_add_f32_e32 v250, v102, v250
	v_mfma_f32_32x32x16_bf16 v[16:31], v[208:211], v[144:147], v[16:31]
	v_cvt_pk_bf16_f32 v150, v108, v109
	v_add_f32_e32 v250, v103, v250
	v_add_f32_e32 v250, v104, v250
	v_mfma_f32_32x32x16_bf16 v[0:15], v[212:215], v[144:147], v[0:15]
	v_cvt_pk_bf16_f32 v151, v110, v111
	v_add_f32_e32 v250, v105, v250
	v_add_f32_e32 v250, v106, v250
	v_mfma_f32_32x32x16_bf16 v[48:63], v[216:219], v[148:151], v[48:63]
	v_cvt_pk_bf16_f32 v152, v112, v113
	v_add_f32_e32 v250, v107, v250
	v_add_f32_e32 v250, v108, v250
	v_mfma_f32_32x32x16_bf16 v[32:47], v[220:223], v[148:151], v[32:47]
	v_cvt_pk_bf16_f32 v153, v114, v115
	v_add_f32_e32 v250, v109, v250
	v_add_f32_e32 v250, v110, v250
	v_mfma_f32_32x32x16_bf16 v[16:31], v[224:227], v[148:151], v[16:31]
	v_cvt_pk_bf16_f32 v154, v116, v117
	v_add_f32_e32 v250, v111, v250
	v_add_f32_e32 v250, v112, v250
	v_mfma_f32_32x32x16_bf16 v[0:15], v[228:231], v[148:151], v[0:15]
	v_cvt_pk_bf16_f32 v155, v118, v119
	v_add_f32_e32 v250, v113, v250
	v_add_f32_e32 v250, v114, v250
	v_add_u32_e32 v248, s67, v177
	ds_read_b128 v[200:203], v248
	ds_read_b128 v[204:207], v248 offset:8192
	v_add_u32_e32 v249, s67, v178
	ds_read_b128 v[208:211], v249
	ds_read_b128 v[212:215], v249 offset:8192
	s_waitcnt lgkmcnt(8)
	v_mfma_f32_32x32x16_bf16 v[48:63], v[64:67], v[152:155], v[48:63]
	v_cvt_pk_bf16_f32 v156, v120, v121
	v_add_f32_e32 v250, v115, v250
	v_add_f32_e32 v250, v116, v250
	v_mfma_f32_32x32x16_bf16 v[32:47], v[68:71], v[152:155], v[32:47]
	v_cvt_pk_bf16_f32 v157, v122, v123
	v_add_f32_e32 v250, v117, v250
	v_add_f32_e32 v250, v118, v250
	v_mfma_f32_32x32x16_bf16 v[16:31], v[72:75], v[152:155], v[16:31]
	v_cvt_pk_bf16_f32 v158, v124, v125
	v_add_f32_e32 v250, v119, v250
	v_add_f32_e32 v250, v120, v250
	v_mfma_f32_32x32x16_bf16 v[0:15], v[76:79], v[152:155], v[0:15]
	v_cvt_pk_bf16_f32 v159, v126, v127
	v_add_f32_e32 v250, v121, v250
	v_add_f32_e32 v250, v122, v250
	v_add_u32_e32 v248, s67, v179
	ds_read_b128 v[216:219], v248
	ds_read_b128 v[220:223], v248 offset:8192
	v_add_u32_e32 v249, s67, v180
	ds_read_b128 v[224:227], v249
	ds_read_b128 v[228:231], v249 offset:8192
	s_waitcnt lgkmcnt(8)
	v_mfma_f32_32x32x16_bf16 v[48:63], v[80:83], v[156:159], v[48:63]
	v_add_f32_e32 v250, v123, v250
	v_add_f32_e32 v250, v124, v250
	v_mfma_f32_32x32x16_bf16 v[32:47], v[84:87], v[156:159], v[32:47]
	v_add_f32_e32 v250, v125, v250
	v_add_f32_e32 v250, v126, v250
	v_mfma_f32_32x32x16_bf16 v[16:31], v[88:91], v[156:159], v[16:31]
	v_add_f32_e32 v250, v127, v250
	v_mfma_f32_32x32x16_bf16 v[0:15], v[92:95], v[156:159], v[0:15]
	v_add_f32_e32 v181, v181, v250
	s_setprio 0
.LBB0_362:
	s_cmp_lt_u32 s66, s16
	s_cselect_b64 s[0:1], -1, 0
	s_cmp_ge_u32 s66, s16
	s_cbranch_scc1 .LBB0_364
	s_setprio 2
	s_waitcnt lgkmcnt(0)
	v_mfma_f32_32x32x16_bf16 v[96:111], v[200:203], v[128:131], v[232:247]
	v_mfma_f32_32x32x16_bf16 v[112:127], v[204:207], v[128:131], v[232:247]
	v_mfma_f32_32x32x16_bf16 v[96:111], v[208:211], v[132:135], v[96:111]
	v_mfma_f32_32x32x16_bf16 v[112:127], v[212:215], v[132:135], v[112:127]
	v_mfma_f32_32x32x16_bf16 v[96:111], v[216:219], v[136:139], v[96:111]
	v_mfma_f32_32x32x16_bf16 v[112:127], v[220:223], v[136:139], v[112:127]
	v_mfma_f32_32x32x16_bf16 v[96:111], v[224:227], v[140:143], v[96:111]
	v_mfma_f32_32x32x16_bf16 v[112:127], v[228:231], v[140:143], v[112:127]
	s_setprio 0
